# phase_norm layer 0: next row's 16 loads prefetched before the current row's compute/stores (copy-in at row start), load wait no longer behind store acks
# speedup vs baseline: 1.0059x; 1.0059x over previous
.LBB0_163:
	s_or_b64 exec, exec, s[0:1]
	v_readlane_b32 s52, v254, 12
	v_readlane_b32 s60, v254, 20
	v_readlane_b32 s61, v254, 21
	v_readlane_b32 s62, v254, 22
	v_readlane_b32 s63, v254, 23
	v_readlane_b32 s64, v254, 24
	v_readlane_b32 s65, v254, 25
	v_readlane_b32 s66, v254, 26
	v_readlane_b32 s67, v254, 27
	v_and_b32_e32 v0, 63, v2
	v_readlane_b32 s60, v254, 28
	v_ashrrev_i32_e32 v1, 4, v2
	v_lshlrev_b32_e32 v2, 2, v0
	v_readlane_b32 s53, v254, 13
	v_readlane_b32 s54, v254, 14
	v_readlane_b32 s55, v254, 15
	v_readlane_b32 s61, v254, 29
	v_and_b32_e32 v1, -4, v1
	v_or_b32_e32 v4, 0x900, v2
	v_or_b32_e32 v6, 0xb00, v2
	v_or_b32_e32 v8, 0xd00, v2
	v_or_b32_e32 v10, 0xf00, v2
	v_or_b32_e32 v12, 0x800, v2
	v_or_b32_e32 v14, 0xa00, v2
	v_or_b32_e32 v16, 0xc00, v2
	v_or_b32_e32 v18, 0xe00, v2
	v_readlane_b32 s62, v254, 30
	v_readlane_b32 s63, v254, 31
	s_mov_b64 s[52:53], s[60:61]
	v_lshl_add_u32 v117, v0, 4, 0
	v_add_u32_e32 v118, s10, v1
	s_mov_b32 s6, 0
	v_lshlrev_b32_e32 v72, 4, v0
	v_lshlrev_b32_e32 v74, 1, v2
	v_lshlrev_b32_e32 v76, 1, v12
	v_mov_b32_e32 v77, v73
	v_lshlrev_b32_e32 v78, 1, v4
	v_mov_b32_e32 v79, v73
	v_lshlrev_b32_e32 v80, 1, v14
	v_mov_b32_e32 v81, v73
	v_lshlrev_b32_e32 v82, 1, v6
	v_mov_b32_e32 v83, v73
	v_lshlrev_b32_e32 v84, 1, v16
	v_mov_b32_e32 v85, v73
	v_lshlrev_b32_e32 v86, 1, v8
	v_mov_b32_e32 v87, v73
	v_lshlrev_b32_e32 v88, 1, v18
	v_mov_b32_e32 v89, v73
	v_lshlrev_b32_e32 v90, 1, v10
	v_mov_b32_e32 v91, v73
	v_mov_b32_e32 v75, v73
	v_readlane_b32 s56, v254, 16
	v_readlane_b32 s57, v254, 17
	s_mov_b64 s[54:55], s[62:63]
	s_waitcnt lgkmcnt(0)
	s_barrier
	v_readlane_b32 s58, v254, 18
	v_readlane_b32 s59, v254, 19
	v_readlane_b32 s64, v254, 32
	v_readlane_b32 s65, v254, 33
	v_readlane_b32 s66, v254, 34
	v_readlane_b32 s67, v254, 35
	v_readlane_b32 s68, v254, 36
	v_readlane_b32 s69, v254, 37
	v_readlane_b32 s70, v254, 38
	v_readlane_b32 s71, v254, 39
	v_readlane_b32 s72, v254, 40
	v_readlane_b32 s73, v254, 41
	v_readlane_b32 s74, v254, 42
	v_readlane_b32 s75, v254, 43
	s_cmpk_lt_i32 s10, 0x1000
	s_cselect_b32 s8, s52, s54
	s_cselect_b32 s9, s53, s55
	s_cselect_b32 s7, 0, 0x1000
	s_mov_b64 s[32:33], 0x1000
	s_mov_b64 s[76:77], 0x2000
	s_mov_b64 s[78:79], 0x3000
	s_mov_b64 s[34:35], 0x4000
	v_subrev_u32_e32 v250, s7, v118
	v_mov_b32_e32 v251, 0
	v_lshlrev_b64 v[250:251], 14, v[250:251]
	v_lshl_add_u64 v[250:251], v[250:251], 0, s[8:9]
	v_lshl_add_u64 v[250:251], v[250:251], 0, v[72:73]
	global_load_dwordx4 v[186:189], v[250:251], off
	global_load_dwordx4 v[190:193], v[250:251], off offset:1024
	global_load_dwordx4 v[194:197], v[250:251], off offset:2048
	global_load_dwordx4 v[198:201], v[250:251], off offset:3072
	v_lshl_add_u64 v[136:137], v[250:251], 0, s[78:79]
	global_load_dwordx4 v[202:205], v[136:137], off
	global_load_dwordx4 v[206:209], v[136:137], off offset:1024
	global_load_dwordx4 v[210:213], v[136:137], off offset:2048
	global_load_dwordx4 v[214:217], v[136:137], off offset:3072
	v_lshl_add_u64 v[136:137], v[250:251], 0, s[32:33]
	global_load_dwordx4 v[218:221], v[136:137], off
	global_load_dwordx4 v[222:225], v[136:137], off offset:1024
	global_load_dwordx4 v[226:229], v[136:137], off offset:2048
	global_load_dwordx4 v[230:233], v[136:137], off offset:3072
	v_lshl_add_u64 v[136:137], v[250:251], 0, s[76:77]
	global_load_dwordx4 v[234:237], v[136:137], off
	global_load_dwordx4 v[238:241], v[136:137], off offset:1024
	global_load_dwordx4 v[242:245], v[136:137], off offset:2048
	global_load_dwordx4 v[246:249], v[136:137], off offset:3072
	s_waitcnt vmcnt(0)
.LBB0_164:
	v_cmp_lt_i32_e32 vcc, v110, v109
	v_add_u32_e32 v8, s6, v118
	s_mov_b64 s[0:1], s[52:53]
	v_cndmask_b32_e32 v0, v108, v110, vcc
	v_cmp_lt_i32_e32 vcc, v111, v109
	s_mov_b64 s[2:3], s[54:55]
	v_add_u32_e32 v10, 0xfffff000, v8
	v_cndmask_b32_e32 v1, v108, v111, vcc
	v_cmp_lt_i32_e32 vcc, v112, v109
	v_ashrrev_i32_e32 v9, 31, v8
	v_lshlrev_b32_e32 v119, 2, v0
	v_cndmask_b32_e32 v2, v108, v112, vcc
	v_cmp_lt_i32_e32 vcc, v113, v109
	v_mov_b32_e32 v12, s3
	v_mov_b32_e32 v13, s1
	v_cndmask_b32_e32 v3, v108, v113, vcc
	v_cmp_lt_i32_e32 vcc, v114, v109
	v_mov_b32_e32 v14, s2
	v_mov_b32_e32 v15, s0
	v_cndmask_b32_e32 v4, v108, v114, vcc
	v_cmp_lt_i32_e32 vcc, v115, v109
	s_movk_i32 s0, 0x2000
	v_lshlrev_b32_e32 v120, 2, v1
	v_cndmask_b32_e32 v5, v108, v115, vcc
	v_cmp_gt_i32_e32 vcc, s13, v8
	v_lshlrev_b32_e32 v121, 2, v2
	v_lshlrev_b32_e32 v122, 2, v3
	v_cndmask_b32_e32 v11, 0, v9, vcc
	v_cndmask_b32_e32 v10, v10, v8, vcc
	v_lshlrev_b64 v[8:9], 13, v[8:9]
	v_cndmask_b32_e32 v13, v12, v13, vcc
	v_cndmask_b32_e32 v12, v14, v15, vcc
	v_lshlrev_b64 v[10:11], 14, v[10:11]
	v_lshl_add_u64 v[106:107], s[56:57], 0, v[8:9]
	v_lshl_add_u64 v[8:9], v[12:13], 0, v[10:11]
	v_lshl_add_u64 v[24:25], v[8:9], 0, v[72:73]
	v_add_co_u32_e32 v40, vcc, s13, v24
	v_lshlrev_b32_e32 v123, 2, v4
	s_nop 0
	v_addc_co_u32_e32 v41, vcc, 0, v25, vcc
	v_add_co_u32_e32 v42, vcc, s0, v24
	v_lshlrev_b32_e32 v124, 2, v5
	s_nop 0
	v_addc_co_u32_e32 v43, vcc, 0, v25, vcc
	ds_read_b128 v[4:7], v117
	ds_read_b128 v[0:3], v117 offset:16384
	v_add_co_u32_e32 v24, vcc, s12, v24
	s_mov_b32 s0, 0x800000
	s_nop 0
	v_addc_co_u32_e32 v25, vcc, 0, v25, vcc
	s_nop 0
	s_nop 0
	s_nop 0
	v_mov_b32_e32 v20, v186
	v_mov_b32_e32 v21, v187
	v_mov_b32_e32 v22, v188
	v_mov_b32_e32 v23, v189
	v_mov_b32_e32 v16, v190
	v_mov_b32_e32 v17, v191
	v_mov_b32_e32 v18, v192
	v_mov_b32_e32 v19, v193
	v_mov_b32_e32 v12, v194
	v_mov_b32_e32 v13, v195
	v_mov_b32_e32 v14, v196
	v_mov_b32_e32 v15, v197
	v_mov_b32_e32 v8, v198
	v_mov_b32_e32 v9, v199
	v_mov_b32_e32 v10, v200
	v_mov_b32_e32 v11, v201
	v_mov_b32_e32 v36, v202
	v_mov_b32_e32 v37, v203
	v_mov_b32_e32 v38, v204
	v_mov_b32_e32 v39, v205
	v_mov_b32_e32 v32, v206
	v_mov_b32_e32 v33, v207
	v_mov_b32_e32 v34, v208
	v_mov_b32_e32 v35, v209
	v_mov_b32_e32 v28, v210
	v_mov_b32_e32 v29, v211
	v_mov_b32_e32 v30, v212
	v_mov_b32_e32 v31, v213
	v_mov_b32_e32 v24, v214
	v_mov_b32_e32 v25, v215
	v_mov_b32_e32 v26, v216
	v_mov_b32_e32 v27, v217
	v_mov_b32_e32 v68, v218
	v_mov_b32_e32 v69, v219
	v_mov_b32_e32 v70, v220
	v_mov_b32_e32 v71, v221
	v_mov_b32_e32 v64, v222
	v_mov_b32_e32 v65, v223
	v_mov_b32_e32 v66, v224
	v_mov_b32_e32 v67, v225
	v_mov_b32_e32 v60, v226
	v_mov_b32_e32 v61, v227
	v_mov_b32_e32 v62, v228
	v_mov_b32_e32 v63, v229
	v_mov_b32_e32 v56, v230
	v_mov_b32_e32 v57, v231
	v_mov_b32_e32 v58, v232
	v_mov_b32_e32 v59, v233
	v_mov_b32_e32 v52, v234
	v_mov_b32_e32 v53, v235
	v_mov_b32_e32 v54, v236
	v_mov_b32_e32 v55, v237
	v_mov_b32_e32 v48, v238
	v_mov_b32_e32 v49, v239
	v_mov_b32_e32 v50, v240
	v_mov_b32_e32 v51, v241
	v_mov_b32_e32 v44, v242
	v_mov_b32_e32 v45, v243
	v_mov_b32_e32 v46, v244
	v_mov_b32_e32 v47, v245
	v_mov_b32_e32 v40, v246
	v_mov_b32_e32 v41, v247
	v_mov_b32_e32 v42, v248
	v_mov_b32_e32 v43, v249
	v_lshl_add_u64 v[96:97], v[106:107], 0, v[74:75]
	v_lshl_add_u64 v[94:95], v[106:107], 0, v[76:77]
	v_lshl_add_u64 v[92:93], v[106:107], 0, v[78:79]
	s_add_i32 s6, s6, 1
	s_cmp_eq_u32 s6, 4
	s_cbranch_scc1 .Lnorm0_nopf
	v_lshl_add_u64 v[250:251], v[250:251], 0, s[34:35]
	global_load_dwordx4 v[186:189], v[250:251], off
	global_load_dwordx4 v[190:193], v[250:251], off offset:1024
	global_load_dwordx4 v[194:197], v[250:251], off offset:2048
	global_load_dwordx4 v[198:201], v[250:251], off offset:3072
	v_lshl_add_u64 v[136:137], v[250:251], 0, s[78:79]
	global_load_dwordx4 v[202:205], v[136:137], off
	global_load_dwordx4 v[206:209], v[136:137], off offset:1024
	global_load_dwordx4 v[210:213], v[136:137], off offset:2048
	global_load_dwordx4 v[214:217], v[136:137], off offset:3072
	v_lshl_add_u64 v[136:137], v[250:251], 0, s[32:33]
	global_load_dwordx4 v[218:221], v[136:137], off
	global_load_dwordx4 v[222:225], v[136:137], off offset:1024
	global_load_dwordx4 v[226:229], v[136:137], off offset:2048
	global_load_dwordx4 v[230:233], v[136:137], off offset:3072
	v_lshl_add_u64 v[136:137], v[250:251], 0, s[76:77]
	global_load_dwordx4 v[234:237], v[136:137], off
	global_load_dwordx4 v[238:241], v[136:137], off offset:1024
	global_load_dwordx4 v[242:245], v[136:137], off offset:2048
	global_load_dwordx4 v[246:249], v[136:137], off offset:3072
.Lnorm0_nopf:
	s_waitcnt lgkmcnt(0)
	v_mov_b32_e32 v100, v37
	v_mov_b32_e32 v101, v33
	v_mov_b32_e32 v98, v36
	v_mov_b32_e32 v99, v32
	v_pk_mul_f32 v[100:101], v[100:101], v[100:101]
	v_mov_b32_e32 v102, v28
	v_pk_fma_f32 v[98:99], v[98:99], v[98:99], v[100:101]
	v_mov_b32_e32 v100, v29
	v_mov_b32_e32 v101, v25
	v_mov_b32_e32 v103, v24
	v_pk_mul_f32 v[100:101], v[100:101], v[100:101]
	v_mul_f32_e32 v104, v21, v21
	v_pk_fma_f32 v[100:101], v[102:103], v[102:103], v[100:101]
	v_mov_b32_e32 v102, v38
	v_mov_b32_e32 v103, v34
	v_pk_fma_f32 v[98:99], v[102:103], v[102:103], v[98:99]
	v_mov_b32_e32 v102, v30
	v_mov_b32_e32 v103, v26
	v_pk_fma_f32 v[100:101], v[102:103], v[102:103], v[100:101]
	v_mov_b32_e32 v102, v39
	v_mov_b32_e32 v103, v35
	v_pk_fma_f32 v[98:99], v[102:103], v[102:103], v[98:99]
	v_mov_b32_e32 v102, v31
	v_mov_b32_e32 v103, v27
	v_pk_fma_f32 v[100:101], v[102:103], v[102:103], v[100:101]
	v_mul_f32_e32 v102, v17, v17
	v_fmac_f32_e32 v104, v20, v20
	v_fmac_f32_e32 v102, v16, v16
	v_fmac_f32_e32 v104, v22, v22
	v_fmac_f32_e32 v102, v18, v18
	v_mul_f32_e32 v103, v13, v13
	v_fmac_f32_e32 v104, v23, v23
	v_fmac_f32_e32 v102, v19, v19
	v_add_f32_e32 v102, v104, v102
	v_mul_f32_e32 v104, v9, v9
	v_fmac_f32_e32 v103, v12, v12
	v_fmac_f32_e32 v104, v8, v8
	v_fmac_f32_e32 v103, v14, v14
	v_fmac_f32_e32 v103, v15, v15
	v_fmac_f32_e32 v104, v10, v10
	v_add_f32_e32 v102, v102, v103
	v_mul_f32_e32 v103, v69, v69
	v_fmac_f32_e32 v104, v11, v11
	v_add_f32_e32 v102, v102, v104
	v_mul_f32_e32 v104, v65, v65
	v_fmac_f32_e32 v103, v68, v68
	v_fmac_f32_e32 v103, v70, v70
	v_fmac_f32_e32 v104, v64, v64
	v_fmac_f32_e32 v103, v71, v71
	v_fmac_f32_e32 v104, v66, v66
	v_add_f32_e32 v102, v102, v103
	v_mul_f32_e32 v103, v61, v61
	v_fmac_f32_e32 v104, v67, v67
	v_add_f32_e32 v102, v102, v104
	v_mul_f32_e32 v104, v57, v57
	v_fmac_f32_e32 v103, v60, v60
	v_fmac_f32_e32 v103, v62, v62
	v_fmac_f32_e32 v104, v56, v56
	v_fmac_f32_e32 v103, v63, v63
	v_fmac_f32_e32 v104, v58, v58
	v_add_f32_e32 v102, v102, v103
	v_mul_f32_e32 v103, v53, v53
	v_fmac_f32_e32 v104, v59, v59
	v_add_f32_e32 v102, v102, v104
	v_mul_f32_e32 v104, v49, v49
	v_fmac_f32_e32 v103, v52, v52
	v_fmac_f32_e32 v103, v54, v54
	v_fmac_f32_e32 v104, v48, v48
	v_fmac_f32_e32 v103, v55, v55
	v_fmac_f32_e32 v104, v50, v50
	v_add_f32_e32 v102, v102, v103
	v_mul_f32_e32 v103, v45, v45
	v_fmac_f32_e32 v104, v51, v51
	v_add_f32_e32 v102, v102, v104
	v_mul_f32_e32 v104, v41, v41
	v_fmac_f32_e32 v103, v44, v44
	v_fmac_f32_e32 v104, v40, v40
	v_fmac_f32_e32 v103, v46, v46
	v_fmac_f32_e32 v104, v42, v42
	v_fmac_f32_e32 v103, v47, v47
	v_fmac_f32_e32 v104, v43, v43
	v_add_f32_e32 v102, v102, v103
	v_add_f32_e32 v102, v102, v104
	v_add_f32_e32 v98, v102, v98
	v_add_f32_e32 v98, v98, v99
	v_add_f32_e32 v98, v98, v100
	v_add_f32_e32 v98, v98, v101
	ds_bpermute_b32 v99, v119, v98
	v_lshl_add_u64 v[104:105], v[106:107], 0, v[80:81]
	v_lshl_add_u64 v[102:103], v[106:107], 0, v[82:83]
	v_lshl_add_u64 v[100:101], v[106:107], 0, v[84:85]
	s_waitcnt lgkmcnt(0)
	v_add_f32_e32 v98, v98, v99
	ds_bpermute_b32 v99, v120, v98
	s_waitcnt lgkmcnt(0)
	v_add_f32_e32 v119, v98, v99
	ds_bpermute_b32 v120, v121, v119
	v_lshl_add_u64 v[98:99], v[106:107], 0, v[86:87]
	s_waitcnt lgkmcnt(0)
	v_add_f32_e32 v119, v119, v120
	ds_bpermute_b32 v120, v122, v119
	s_waitcnt lgkmcnt(0)
	v_add_f32_e32 v119, v119, v120
	ds_bpermute_b32 v120, v123, v119
	s_waitcnt lgkmcnt(0)
	v_add_f32_e32 v119, v119, v120
	ds_bpermute_b32 v120, v124, v119
	s_waitcnt lgkmcnt(0)
	v_add_f32_e32 v119, v119, v120
	v_fmamk_f32 v119, v119, 0x39800000, v116
	v_mul_f32_e32 v120, 0x4b800000, v119
	v_cmp_gt_f32_e32 vcc, s0, v119
	s_nop 1
	v_cndmask_b32_e32 v119, v119, v120, vcc
	v_rsq_f32_e32 v119, v119
	s_nop 0
	v_mul_f32_e32 v120, 0x45800000, v119
	v_cndmask_b32_e32 v135, v119, v120, vcc
	v_mul_f32_e32 v131, v20, v135
	v_mul_f32_e32 v132, v21, v135
	v_mul_f32_e32 v133, v22, v135
	v_mul_f32_e32 v134, v23, v135
	v_fma_f32 v0, v4, v131, v0
	v_fma_f32 v1, v5, v132, v1
	v_fma_f32 v2, v6, v133, v2
	v_fmac_f32_e32 v3, v7, v134
	v_mul_f32_e32 v123, v12, v135
	v_mul_f32_e32 v124, v13, v135
	v_mul_f32_e32 v12, v24, v135
	v_mul_f32_e32 v13, v25, v135
	v_cvt_pk_bf16_f32 v24, v0, v1
	v_cvt_pk_bf16_f32 v25, v2, v3
	ds_read_b128 v[0:3], v117 offset:1024
	ds_read_b128 v[4:7], v117 offset:17408
	v_mul_f32_e32 v127, v16, v135
	v_mul_f32_e32 v128, v17, v135
	v_mul_f32_e32 v129, v18, v135
	v_mul_f32_e32 v130, v19, v135
	s_waitcnt lgkmcnt(0)
	v_fma_f32 v0, v127, v0, v4
	v_fma_f32 v1, v128, v1, v5
	v_fma_f32 v2, v129, v2, v6
	v_fmac_f32_e32 v7, v130, v3
	global_store_dwordx2 v[96:97], v[24:25], off
	v_cvt_pk_bf16_f32 v24, v0, v1
	v_cvt_pk_bf16_f32 v25, v2, v7
	ds_read_b128 v[0:3], v117 offset:2048
	ds_read_b128 v[4:7], v117 offset:18432
	v_mul_f32_e32 v125, v14, v135
	v_mul_f32_e32 v126, v15, v135
	global_store_dwordx2 v[96:97], v[24:25], off offset:512
	v_mul_f32_e32 v119, v8, v135
	s_waitcnt lgkmcnt(0)
	v_fma_f32 v0, v123, v0, v4
	v_fma_f32 v1, v124, v1, v5
	v_fma_f32 v2, v125, v2, v6
	v_fmac_f32_e32 v7, v126, v3
	v_cvt_pk_bf16_f32 v24, v0, v1
	v_cvt_pk_bf16_f32 v25, v2, v7
	ds_read_b128 v[0:3], v117 offset:3072
	ds_read_b128 v[4:7], v117 offset:19456
	v_mul_f32_e32 v120, v9, v135
	v_mul_f32_e32 v121, v10, v135
	v_mul_f32_e32 v122, v11, v135
	global_store_dwordx2 v[96:97], v[24:25], off offset:1024
	s_waitcnt lgkmcnt(0)
	v_fma_f32 v0, v119, v0, v4
	v_fma_f32 v1, v120, v1, v5
	v_fma_f32 v2, v121, v2, v6
	v_fmac_f32_e32 v7, v122, v3
	v_cvt_pk_bf16_f32 v24, v0, v1
	v_cvt_pk_bf16_f32 v25, v2, v7
	ds_read_b128 v[0:3], v117 offset:4096
	ds_read_b128 v[4:7], v117 offset:20480
	v_mul_f32_e32 v68, v68, v135
	v_mul_f32_e32 v69, v69, v135
	v_mul_f32_e32 v70, v70, v135
	v_mul_f32_e32 v71, v71, v135
	s_waitcnt lgkmcnt(0)
	v_fma_f32 v0, v68, v0, v4
	v_fma_f32 v1, v69, v1, v5
	v_fma_f32 v2, v70, v2, v6
	v_fmac_f32_e32 v7, v71, v3
	global_store_dwordx2 v[96:97], v[24:25], off offset:1536
	v_cvt_pk_bf16_f32 v24, v0, v1
	v_cvt_pk_bf16_f32 v25, v2, v7
	ds_read_b128 v[0:3], v117 offset:5120
	ds_read_b128 v[4:7], v117 offset:21504
	v_mul_f32_e32 v64, v64, v135
	v_mul_f32_e32 v65, v65, v135
	v_mul_f32_e32 v66, v66, v135
	v_mul_f32_e32 v67, v67, v135
	s_waitcnt lgkmcnt(0)
	v_fma_f32 v0, v64, v0, v4
	v_fma_f32 v1, v65, v1, v5
	v_fma_f32 v2, v66, v2, v6
	v_fmac_f32_e32 v7, v67, v3
	global_store_dwordx2 v[96:97], v[24:25], off offset:2048
	v_cvt_pk_bf16_f32 v24, v0, v1
	v_cvt_pk_bf16_f32 v25, v2, v7
	ds_read_b128 v[0:3], v117 offset:6144
	ds_read_b128 v[4:7], v117 offset:22528
	v_mul_f32_e32 v60, v60, v135
	v_mul_f32_e32 v61, v61, v135
	v_mul_f32_e32 v62, v62, v135
	v_mul_f32_e32 v63, v63, v135
	s_waitcnt lgkmcnt(0)
	v_fma_f32 v0, v60, v0, v4
	v_fma_f32 v1, v61, v1, v5
	v_fma_f32 v2, v62, v2, v6
	v_fmac_f32_e32 v7, v63, v3
	global_store_dwordx2 v[96:97], v[24:25], off offset:2560
	v_cvt_pk_bf16_f32 v24, v0, v1
	v_cvt_pk_bf16_f32 v25, v2, v7
	ds_read_b128 v[0:3], v117 offset:7168
	ds_read_b128 v[4:7], v117 offset:23552
	v_mul_f32_e32 v56, v56, v135
	v_mul_f32_e32 v57, v57, v135
	v_mul_f32_e32 v58, v58, v135
	v_mul_f32_e32 v59, v59, v135
	s_waitcnt lgkmcnt(0)
	v_fma_f32 v0, v56, v0, v4
	v_fma_f32 v1, v57, v1, v5
	v_fma_f32 v2, v58, v2, v6
	v_fmac_f32_e32 v7, v59, v3
	global_store_dwordx2 v[96:97], v[24:25], off offset:3072
	v_cvt_pk_bf16_f32 v24, v0, v1
	v_cvt_pk_bf16_f32 v25, v2, v7
	ds_read_b128 v[0:3], v117 offset:8192
	ds_read_b128 v[4:7], v117 offset:24576
	v_mul_f32_e32 v52, v52, v135
	v_mul_f32_e32 v53, v53, v135
	v_mul_f32_e32 v54, v54, v135
	v_mul_f32_e32 v55, v55, v135
	s_waitcnt lgkmcnt(0)
	v_fma_f32 v0, v52, v0, v4
	v_fma_f32 v1, v53, v1, v5
	v_fma_f32 v2, v54, v2, v6
	v_fmac_f32_e32 v7, v55, v3
	global_store_dwordx2 v[96:97], v[24:25], off offset:3584
	v_cvt_pk_bf16_f32 v24, v0, v1
	v_cvt_pk_bf16_f32 v25, v2, v7
	ds_read_b128 v[0:3], v117 offset:9216
	ds_read_b128 v[4:7], v117 offset:25600
	v_mul_f32_e32 v48, v48, v135
	v_mul_f32_e32 v49, v49, v135
	v_mul_f32_e32 v50, v50, v135
	v_mul_f32_e32 v51, v51, v135
	s_waitcnt lgkmcnt(0)
	v_fma_f32 v0, v48, v0, v4
	v_fma_f32 v1, v49, v1, v5
	v_fma_f32 v2, v50, v2, v6
	v_fmac_f32_e32 v7, v51, v3
	global_store_dwordx2 v[94:95], v[24:25], off
	v_cvt_pk_bf16_f32 v24, v0, v1
	v_cvt_pk_bf16_f32 v25, v2, v7
	ds_read_b128 v[0:3], v117 offset:10240
	ds_read_b128 v[4:7], v117 offset:26624
	v_mul_f32_e32 v44, v44, v135
	v_mul_f32_e32 v45, v45, v135
	v_mul_f32_e32 v46, v46, v135
	v_mul_f32_e32 v47, v47, v135
	s_waitcnt lgkmcnt(0)
	v_fma_f32 v0, v44, v0, v4
	v_fma_f32 v1, v45, v1, v5
	v_fma_f32 v2, v46, v2, v6
	v_fmac_f32_e32 v7, v47, v3
	global_store_dwordx2 v[92:93], v[24:25], off
	v_cvt_pk_bf16_f32 v24, v0, v1
	v_cvt_pk_bf16_f32 v25, v2, v7
	ds_read_b128 v[0:3], v117 offset:11264
	ds_read_b128 v[4:7], v117 offset:27648
	v_mul_f32_e32 v40, v40, v135
	v_mul_f32_e32 v41, v41, v135
	v_mul_f32_e32 v42, v42, v135
	v_mul_f32_e32 v43, v43, v135
	s_waitcnt lgkmcnt(0)
	v_fma_f32 v0, v40, v0, v4
	v_fma_f32 v1, v41, v1, v5
	v_fma_f32 v2, v42, v2, v6
	v_fmac_f32_e32 v7, v43, v3
	global_store_dwordx2 v[104:105], v[24:25], off
	v_cvt_pk_bf16_f32 v24, v0, v1
	v_cvt_pk_bf16_f32 v25, v2, v7
	ds_read_b128 v[0:3], v117 offset:12288
	ds_read_b128 v[4:7], v117 offset:28672
	v_mul_f32_e32 v36, v36, v135
	v_mul_f32_e32 v37, v37, v135
	v_mul_f32_e32 v38, v38, v135
	v_mul_f32_e32 v39, v39, v135
	s_waitcnt lgkmcnt(0)
	v_fma_f32 v0, v36, v0, v4
	v_fma_f32 v1, v37, v1, v5
	v_fma_f32 v2, v38, v2, v6
	v_fmac_f32_e32 v7, v39, v3
	global_store_dwordx2 v[102:103], v[24:25], off
	v_cvt_pk_bf16_f32 v24, v0, v1
	v_cvt_pk_bf16_f32 v25, v2, v7
	ds_read_b128 v[0:3], v117 offset:13312
	ds_read_b128 v[4:7], v117 offset:29696
	v_mul_f32_e32 v20, v32, v135
	v_mul_f32_e32 v21, v33, v135
	v_mul_f32_e32 v22, v34, v135
	v_mul_f32_e32 v23, v35, v135
	s_waitcnt lgkmcnt(0)
	v_fma_f32 v0, v20, v0, v4
	v_fma_f32 v1, v21, v1, v5
	v_fma_f32 v2, v22, v2, v6
	v_fmac_f32_e32 v7, v23, v3
	global_store_dwordx2 v[100:101], v[24:25], off
	v_cvt_pk_bf16_f32 v20, v0, v1
	v_cvt_pk_bf16_f32 v21, v2, v7
	ds_read_b128 v[0:3], v117 offset:14336
	ds_read_b128 v[4:7], v117 offset:30720
	v_mul_f32_e32 v16, v28, v135
	v_mul_f32_e32 v17, v29, v135
	v_mul_f32_e32 v18, v30, v135
	v_mul_f32_e32 v19, v31, v135
	s_waitcnt lgkmcnt(0)
	v_fma_f32 v0, v16, v0, v4
	v_fma_f32 v1, v17, v1, v5
	v_fma_f32 v2, v18, v2, v6
	v_fmac_f32_e32 v7, v19, v3
	global_store_dwordx2 v[98:99], v[20:21], off
	v_cvt_pk_bf16_f32 v16, v0, v1
	v_cvt_pk_bf16_f32 v17, v2, v7
	ds_read_b128 v[0:3], v117 offset:15360
	ds_read_b128 v[4:7], v117 offset:31744
	v_mul_f32_e32 v14, v26, v135
	v_mul_f32_e32 v15, v27, v135
	v_lshl_add_u64 v[10:11], v[106:107], 0, v[88:89]
	v_lshl_add_u64 v[8:9], v[106:107], 0, v[90:91]
	s_waitcnt lgkmcnt(0)
	v_fma_f32 v0, v12, v0, v4
	v_fma_f32 v1, v13, v1, v5
	global_store_dwordx2 v[10:11], v[16:17], off
	v_fma_f32 v2, v14, v2, v6
	v_fmac_f32_e32 v7, v15, v3
	v_cvt_pk_bf16_f32 v0, v0, v1
	v_cvt_pk_bf16_f32 v1, v2, v7
	global_store_dwordx2 v[8:9], v[0:1], off
	s_waitcnt vmcnt(16)
	s_cbranch_scc0 .LBB0_164
	s_add_i32 s14, s14, s84
	s_add_i32 s10, s10, s11
	s_cmpk_gt_i32 s14, 0xff
	s_cbranch_scc0 .LBB0_160
